# mLSTM chunk phase: K-fragment loads batched per block, LDS fragment reads batched with counted lgkmcnt, staging loops unrolled (one wait)
# speedup vs baseline: 1.0214x; 1.0214x over previous
.LBB0_1252:
	s_or_b64 exec, exec, s[56:57]
	s_lshl_b32 s14, s65, 1
	v_lshl_add_u64 v[2:3], v[66:67], 0, s[14:15]
	v_or_b32_e32 v0, s38, v60
	v_mad_u64_u32 v[56:57], s[56:57], v0, s63, v[2:3]
	s_mul_i32 s14, s39, 0x600
	v_add_u32_e32 v91, v73, v62
	v_add_u32_e32 v57, s14, v57
	s_waitcnt lgkmcnt(0)
	s_barrier
	ds_read_b128 v[32:35], v71
	ds_read_b128 v[28:31], v71 offset:64
	ds_read_b128 v[24:27], v71 offset:128
	ds_read_b128 v[20:23], v71 offset:192
	ds_read_b128 v[16:19], v71 offset:256
	ds_read_b128 v[12:15], v71 offset:320
	ds_read_b128 v[8:11], v91 offset:51712
	flat_load_dwordx4 v[36:39], v[56:57]
	flat_load_dwordx4 v[40:43], v[56:57] offset:64
	flat_load_dwordx4 v[44:47], v[56:57] offset:128
	flat_load_dwordx4 v[48:51], v[56:57] offset:192
	flat_load_dwordx4 v[52:55], v[56:57] offset:256
	s_nop 0
	flat_load_dwordx4 v[56:59], v[56:57] offset:320
	ds_read_b32 v0, v75 offset:51200
	s_waitcnt vmcnt(0) lgkmcnt(0)
	v_mfma_f32_16x16x32_bf16 v[36:39], v[32:35], v[36:39], 0
	v_mfma_f32_16x16x32_bf16 v[36:39], v[28:31], v[40:43], v[36:39]
	v_sub_f32_e32 v40, v0, v8
	v_mul_f32_e32 v40, 0x3fb8aa3b, v40
	v_exp_f32_e32 v40, v40
	v_mfma_f32_16x16x32_bf16 v[36:39], v[24:27], v[44:47], v[36:39]
	v_mov_b32_e32 v41, 0
	v_mfma_f32_16x16x32_bf16 v[36:39], v[20:23], v[48:51], v[36:39]
	v_mfma_f32_16x16x32_bf16 v[36:39], v[16:19], v[52:55], v[36:39]
	v_mfma_f32_16x16x32_bf16 v[36:39], v[12:15], v[56:59], v[36:39]
	s_nop 7
	v_mul_f32_e32 v36, v36, v40
	v_cndmask_b32_e64 v36, v36, 0, s[22:23]
	v_bfe_u32 v40, v36, 16, 1
	v_add3_u32 v36, v36, v40, s64
	ds_write_b16_d16_hi v101, v36 offset:55808
	v_sub_f32_e32 v36, v0, v9
	v_mul_f32_e32 v36, 0x3fb8aa3b, v36
	v_exp_f32_e32 v36, v36
	v_mov_b32_e32 v40, 0
	v_mul_f32_e32 v36, v37, v36
	v_cndmask_b32_e64 v36, v36, 0, s[24:25]
	v_bfe_u32 v37, v36, 16, 1
	v_add3_u32 v36, v36, v37, s64
	ds_write_b16_d16_hi v101, v36 offset:56080
	v_sub_f32_e32 v36, v0, v10
	v_mul_f32_e32 v36, 0x3fb8aa3b, v36
	v_exp_f32_e32 v36, v36
	v_sub_f32_e32 v0, v0, v11
	v_mul_f32_e32 v0, 0x3fb8aa3b, v0
	v_exp_f32_e32 v0, v0
	v_mul_f32_e32 v36, v38, v36
	v_cndmask_b32_e64 v36, v36, 0, s[26:27]
	v_bfe_u32 v37, v36, 16, 1
	v_mul_f32_e32 v0, v39, v0
	v_add3_u32 v36, v36, v37, s64
	v_cndmask_b32_e64 v0, v0, 0, s[28:29]
	ds_write_b16_d16_hi v101, v36 offset:56352
	v_bfe_u32 v36, v0, 16, 1
	v_add3_u32 v0, v0, v36, s64
	v_mov_b32_e32 v36, 0
	v_mov_b32_e32 v38, 0
	v_mov_b32_e32 v39, 0
	ds_write_b16_d16_hi v101, v0 offset:56624
	s_and_saveexec_b64 s[56:57], s[30:31]
	s_cbranch_execz .LBB0_1254
	v_or_b32_e32 v0, s38, v68
	v_mad_u64_u32 v[46:47], s[58:59], v0, s63, v[2:3]
	v_add_u32_e32 v47, s14, v47
	global_load_dwordx4 v[38:41], v[46:47], off
	global_load_dwordx4 v[42:45], v[46:47], off offset:64
	global_load_dwordx4 v[148:151], v[46:47], off offset:128
	global_load_dwordx4 v[152:155], v[46:47], off offset:192
	global_load_dwordx4 v[156:159], v[46:47], off offset:256
	global_load_dwordx4 v[160:163], v[46:47], off offset:320
	s_waitcnt vmcnt(0) lgkmcnt(0)
	v_mfma_f32_16x16x32_bf16 v[38:41], v[32:35], v[38:41], 0
	v_mfma_f32_16x16x32_bf16 v[38:41], v[28:31], v[42:45], v[38:41]
	v_mfma_f32_16x16x32_bf16 v[38:41], v[24:27], v[148:151], v[38:41]
	v_mfma_f32_16x16x32_bf16 v[38:41], v[20:23], v[152:155], v[38:41]
	v_mfma_f32_16x16x32_bf16 v[38:41], v[16:19], v[156:159], v[38:41]
	v_mfma_f32_16x16x32_bf16 v[38:41], v[12:15], v[160:163], v[38:41]
.LBB0_1254:
	s_or_b64 exec, exec, s[56:57]
	ds_read_b32 v0, v75 offset:51264
	v_readlane_b32 s40, v252, 30
	v_readlane_b32 s41, v252, 31
	s_waitcnt lgkmcnt(0)
	v_sub_f32_e32 v37, v0, v8
	v_mul_f32_e32 v37, 0x3fb8aa3b, v37
	v_exp_f32_e32 v37, v37
	s_nop 0
	v_mul_f32_e32 v37, v38, v37
	v_cndmask_b32_e64 v37, v37, 0, s[40:41]
	v_bfe_u32 v38, v37, 16, 1
	v_add3_u32 v37, v37, v38, s64
	ds_write_b16_d16_hi v104, v37 offset:55840
	v_sub_f32_e32 v37, v0, v9
	v_mul_f32_e32 v37, 0x3fb8aa3b, v37
	v_exp_f32_e32 v37, v37
	v_readlane_b32 s40, v252, 32
	v_readlane_b32 s41, v252, 33
	v_mul_f32_e32 v37, v39, v37
	s_nop 0
	v_cndmask_b32_e64 v37, v37, 0, s[40:41]
	v_bfe_u32 v38, v37, 16, 1
	v_add3_u32 v37, v37, v38, s64
	ds_write_b16_d16_hi v104, v37 offset:56112
	v_sub_f32_e32 v37, v0, v10
	v_mul_f32_e32 v37, 0x3fb8aa3b, v37
	v_exp_f32_e32 v37, v37
	v_sub_f32_e32 v0, v0, v11
	v_mul_f32_e32 v0, 0x3fb8aa3b, v0
	v_exp_f32_e32 v0, v0
	v_readlane_b32 s40, v252, 34
	v_mul_f32_e32 v37, v40, v37
	v_readlane_b32 s41, v252, 35
	v_mul_f32_e32 v0, v41, v0
	v_mov_b32_e32 v39, 0
	v_cndmask_b32_e64 v37, v37, 0, s[40:41]
	v_readlane_b32 s40, v252, 36
	v_bfe_u32 v38, v37, 16, 1
	v_readlane_b32 s41, v252, 37
	v_add3_u32 v37, v37, v38, s64
	ds_write_b16_d16_hi v104, v37 offset:56384
	v_cndmask_b32_e64 v0, v0, 0, s[40:41]
	v_bfe_u32 v37, v0, 16, 1
	v_readlane_b32 s40, v252, 20
	v_add3_u32 v0, v0, v37, s64
	v_mov_b32_e32 v38, 0
	v_mov_b32_e32 v40, 0
	v_mov_b32_e32 v41, 0
	v_readlane_b32 s41, v252, 21
	ds_write_b16_d16_hi v104, v0 offset:56656
	s_and_saveexec_b64 s[56:57], s[40:41]
	s_cbranch_execz .LBB0_1256
	v_or_b32_e32 v0, s38, v70
	v_mad_u64_u32 v[46:47], s[58:59], v0, s63, v[2:3]
	v_add_u32_e32 v47, s14, v47
	global_load_dwordx4 v[38:41], v[46:47], off
	global_load_dwordx4 v[42:45], v[46:47], off offset:64
	global_load_dwordx4 v[148:151], v[46:47], off offset:128
	global_load_dwordx4 v[152:155], v[46:47], off offset:192
	global_load_dwordx4 v[156:159], v[46:47], off offset:256
	global_load_dwordx4 v[160:163], v[46:47], off offset:320
	s_waitcnt vmcnt(0) lgkmcnt(0)
	v_mfma_f32_16x16x32_bf16 v[38:41], v[32:35], v[38:41], 0
	v_mfma_f32_16x16x32_bf16 v[38:41], v[28:31], v[42:45], v[38:41]
	v_mfma_f32_16x16x32_bf16 v[38:41], v[24:27], v[148:151], v[38:41]
	v_mfma_f32_16x16x32_bf16 v[38:41], v[20:23], v[152:155], v[38:41]
	v_mfma_f32_16x16x32_bf16 v[38:41], v[16:19], v[156:159], v[38:41]
	v_mfma_f32_16x16x32_bf16 v[38:41], v[12:15], v[160:163], v[38:41]
.LBB0_1256:
	s_or_b64 exec, exec, s[56:57]
	ds_read_b32 v0, v75 offset:51328
	v_readlane_b32 s40, v252, 38
	v_readlane_b32 s41, v252, 39
	s_waitcnt lgkmcnt(0)
	v_sub_f32_e32 v37, v0, v8
	v_mul_f32_e32 v37, 0x3fb8aa3b, v37
	v_exp_f32_e32 v37, v37
	s_nop 0
	v_mul_f32_e32 v37, v38, v37
	v_cndmask_b32_e64 v37, v37, 0, s[40:41]
	v_bfe_u32 v38, v37, 16, 1
	v_add3_u32 v37, v37, v38, s64
	ds_write_b16_d16_hi v104, v37 offset:55872
	v_sub_f32_e32 v37, v0, v9
	v_mul_f32_e32 v37, 0x3fb8aa3b, v37
	v_exp_f32_e32 v37, v37
	v_readlane_b32 s40, v252, 40
	v_readlane_b32 s41, v252, 41
	v_mul_f32_e32 v37, v39, v37
	s_nop 0
	v_cndmask_b32_e64 v37, v37, 0, s[40:41]
	v_bfe_u32 v38, v37, 16, 1
	v_add3_u32 v37, v37, v38, s64
	ds_write_b16_d16_hi v104, v37 offset:56144
	v_sub_f32_e32 v37, v0, v10
	v_mul_f32_e32 v37, 0x3fb8aa3b, v37
	v_exp_f32_e32 v37, v37
	v_sub_f32_e32 v0, v0, v11
	v_mul_f32_e32 v0, 0x3fb8aa3b, v0
	v_exp_f32_e32 v0, v0
	v_mul_f32_e32 v37, v40, v37
	v_cndmask_b32_e64 v37, v37, 0, s[8:9]
	v_bfe_u32 v38, v37, 16, 1
	v_mul_f32_e32 v0, v41, v0
	v_add3_u32 v37, v37, v38, s64
	v_cndmask_b32_e64 v0, v0, 0, s[10:11]
	ds_write_b16_d16_hi v104, v37 offset:56416
	v_bfe_u32 v37, v0, 16, 1
	v_readlane_b32 s40, v252, 22
	v_add3_u32 v0, v0, v37, s64
	v_mov_b32_e32 v37, 0
	v_mov_b32_e32 v38, 0
	v_mov_b32_e32 v39, 0
	v_readlane_b32 s41, v252, 23
	ds_write_b16_d16_hi v104, v0 offset:56688
	s_and_saveexec_b64 s[56:57], s[40:41]
	s_cbranch_execz .LBB0_1258
	v_or_b32_e32 v0, s38, v72
	v_mad_u64_u32 v[44:45], s[58:59], v0, s63, v[2:3]
	v_add_u32_e32 v45, s14, v45
	global_load_dwordx4 v[36:39], v[44:45], off
	global_load_dwordx4 v[40:43], v[44:45], off offset:64
	global_load_dwordx4 v[148:151], v[44:45], off offset:128
	global_load_dwordx4 v[152:155], v[44:45], off offset:192
	global_load_dwordx4 v[156:159], v[44:45], off offset:256
	global_load_dwordx4 v[160:163], v[44:45], off offset:320
	s_waitcnt vmcnt(0) lgkmcnt(0)
	v_mfma_f32_16x16x32_bf16 v[36:39], v[32:35], v[36:39], 0
	v_mfma_f32_16x16x32_bf16 v[36:39], v[28:31], v[40:43], v[36:39]
	v_mfma_f32_16x16x32_bf16 v[36:39], v[24:27], v[148:151], v[36:39]
	v_mfma_f32_16x16x32_bf16 v[36:39], v[20:23], v[152:155], v[36:39]
	v_mfma_f32_16x16x32_bf16 v[36:39], v[16:19], v[156:159], v[36:39]
	v_mfma_f32_16x16x32_bf16 v[36:39], v[12:15], v[160:163], v[36:39]
.LBB0_1258:
	s_or_b64 exec, exec, s[56:57]
	ds_read_b32 v0, v75 offset:51392
	v_readlane_b32 s40, v252, 42
	v_readlane_b32 s41, v252, 43
	v_mov_b32_e32 v41, 0
	s_waitcnt lgkmcnt(0)
	v_sub_f32_e32 v40, v0, v8
	v_mul_f32_e32 v40, 0x3fb8aa3b, v40
	v_exp_f32_e32 v40, v40
	s_nop 0
	v_mul_f32_e32 v36, v36, v40
	v_cndmask_b32_e64 v36, v36, 0, s[40:41]
	v_bfe_u32 v40, v36, 16, 1
	v_add3_u32 v36, v36, v40, s64
	ds_write_b16_d16_hi v104, v36 offset:55904
	v_sub_f32_e32 v36, v0, v9
	v_mul_f32_e32 v36, 0x3fb8aa3b, v36
	v_exp_f32_e32 v36, v36
	v_readlane_b32 s40, v252, 44
	v_readlane_b32 s41, v252, 45
	v_mov_b32_e32 v40, 0
	v_mul_f32_e32 v36, v37, v36
	v_cndmask_b32_e64 v36, v36, 0, s[40:41]
	v_bfe_u32 v37, v36, 16, 1
	v_add3_u32 v36, v36, v37, s64
	ds_write_b16_d16_hi v104, v36 offset:56176
	v_sub_f32_e32 v36, v0, v10
	v_mul_f32_e32 v36, 0x3fb8aa3b, v36
	v_exp_f32_e32 v36, v36
	v_sub_f32_e32 v0, v0, v11
	v_mul_f32_e32 v0, 0x3fb8aa3b, v0
	v_exp_f32_e32 v0, v0
	v_mul_f32_e32 v36, v38, v36
	v_cndmask_b32_e64 v36, v36, 0, s[86:87]
	v_bfe_u32 v37, v36, 16, 1
	v_mul_f32_e32 v0, v39, v0
	v_add3_u32 v36, v36, v37, s64
	v_cndmask_b32_e64 v0, v0, 0, s[88:89]
	ds_write_b16_d16_hi v104, v36 offset:56448
	v_bfe_u32 v36, v0, 16, 1
	v_add3_u32 v0, v0, v36, s64
	v_mov_b32_e32 v36, 0
	v_mov_b32_e32 v38, 0
	v_mov_b32_e32 v39, 0
	ds_write_b16_d16_hi v104, v0 offset:56720
	s_and_saveexec_b64 s[56:57], s[34:35]
	s_cbranch_execz .LBB0_1260
	v_or_b32_e32 v0, s38, v74
	v_mad_u64_u32 v[46:47], s[58:59], v0, s63, v[2:3]
	v_add_u32_e32 v47, s14, v47
	global_load_dwordx4 v[38:41], v[46:47], off
	global_load_dwordx4 v[42:45], v[46:47], off offset:64
	global_load_dwordx4 v[148:151], v[46:47], off offset:128
	global_load_dwordx4 v[152:155], v[46:47], off offset:192
	global_load_dwordx4 v[156:159], v[46:47], off offset:256
	global_load_dwordx4 v[160:163], v[46:47], off offset:320
	s_waitcnt vmcnt(0) lgkmcnt(0)
	v_mfma_f32_16x16x32_bf16 v[38:41], v[32:35], v[38:41], 0
	v_mfma_f32_16x16x32_bf16 v[38:41], v[28:31], v[42:45], v[38:41]
	v_mfma_f32_16x16x32_bf16 v[38:41], v[24:27], v[148:151], v[38:41]
	v_mfma_f32_16x16x32_bf16 v[38:41], v[20:23], v[152:155], v[38:41]
	v_mfma_f32_16x16x32_bf16 v[38:41], v[16:19], v[156:159], v[38:41]
	v_mfma_f32_16x16x32_bf16 v[38:41], v[12:15], v[160:163], v[38:41]
.LBB0_1260:
	s_or_b64 exec, exec, s[56:57]
	ds_read_b32 v0, v75 offset:51456
	v_readlane_b32 s40, v252, 24
	v_readlane_b32 s41, v252, 25
	s_waitcnt lgkmcnt(0)
	v_sub_f32_e32 v37, v0, v8
	v_mul_f32_e32 v37, 0x3fb8aa3b, v37
	v_exp_f32_e32 v37, v37
	s_nop 0
	v_mul_f32_e32 v37, v38, v37
	v_cndmask_b32_e64 v37, v37, 0, s[90:91]
	v_bfe_u32 v38, v37, 16, 1
	v_add3_u32 v37, v37, v38, s64
	ds_write_b16_d16_hi v104, v37 offset:55936
	v_sub_f32_e32 v37, v0, v9
	v_mul_f32_e32 v37, 0x3fb8aa3b, v37
	v_exp_f32_e32 v37, v37
	s_nop 0
	v_mul_f32_e32 v37, v39, v37
	v_cndmask_b32_e64 v37, v37, 0, s[92:93]
	v_bfe_u32 v38, v37, 16, 1
	v_add3_u32 v37, v37, v38, s64
	ds_write_b16_d16_hi v104, v37 offset:56208
	v_sub_f32_e32 v37, v0, v10
	v_mul_f32_e32 v37, 0x3fb8aa3b, v37
	v_exp_f32_e32 v37, v37
	v_sub_f32_e32 v0, v0, v11
	v_mul_f32_e32 v0, 0x3fb8aa3b, v0
	v_exp_f32_e32 v0, v0
	v_mul_f32_e32 v37, v40, v37
	v_cndmask_b32_e64 v37, v37, 0, s[94:95]
	v_bfe_u32 v38, v37, 16, 1
	v_mul_f32_e32 v0, v41, v0
	v_add3_u32 v37, v37, v38, s64
	v_cndmask_b32_e64 v0, v0, 0, s[96:97]
	ds_write_b16_d16_hi v104, v37 offset:56480
	v_bfe_u32 v37, v0, 16, 1
	v_add3_u32 v0, v0, v37, s64
	v_mov_b32_e32 v37, 0
	v_mov_b32_e32 v38, 0
	v_mov_b32_e32 v39, 0
	ds_write_b16_d16_hi v104, v0 offset:56752
	s_and_saveexec_b64 s[56:57], s[40:41]
	s_cbranch_execz .LBB0_1262
	v_or_b32_e32 v0, s38, v76
	v_mad_u64_u32 v[44:45], s[58:59], v0, s63, v[2:3]
	v_add_u32_e32 v45, s14, v45
	global_load_dwordx4 v[36:39], v[44:45], off
	global_load_dwordx4 v[40:43], v[44:45], off offset:64
	global_load_dwordx4 v[148:151], v[44:45], off offset:128
	global_load_dwordx4 v[152:155], v[44:45], off offset:192
	global_load_dwordx4 v[156:159], v[44:45], off offset:256
	global_load_dwordx4 v[160:163], v[44:45], off offset:320
	s_waitcnt vmcnt(0) lgkmcnt(0)
	v_mfma_f32_16x16x32_bf16 v[36:39], v[32:35], v[36:39], 0
	v_mfma_f32_16x16x32_bf16 v[36:39], v[28:31], v[40:43], v[36:39]
	v_mfma_f32_16x16x32_bf16 v[36:39], v[24:27], v[148:151], v[36:39]
	v_mfma_f32_16x16x32_bf16 v[36:39], v[20:23], v[152:155], v[36:39]
	v_mfma_f32_16x16x32_bf16 v[36:39], v[16:19], v[156:159], v[36:39]
	v_mfma_f32_16x16x32_bf16 v[36:39], v[12:15], v[160:163], v[36:39]
.LBB0_1262:
	s_or_b64 exec, exec, s[56:57]
	ds_read_b32 v0, v75 offset:51520
	v_readlane_b32 s40, v252, 26
	v_mov_b32_e32 v41, 0
	v_readlane_b32 s41, v252, 27
	s_waitcnt lgkmcnt(0)
	v_sub_f32_e32 v40, v0, v8
	v_mul_f32_e32 v40, 0x3fb8aa3b, v40
	v_exp_f32_e32 v40, v40
	s_nop 0
	v_mul_f32_e32 v36, v36, v40
	v_cndmask_b32_e64 v36, v36, 0, s[6:7]
	v_bfe_u32 v40, v36, 16, 1
	v_add3_u32 v36, v36, v40, s64
	ds_write_b16_d16_hi v104, v36 offset:55968
	v_sub_f32_e32 v36, v0, v9
	v_mul_f32_e32 v36, 0x3fb8aa3b, v36
	v_exp_f32_e32 v36, v36
	v_mov_b32_e32 v40, 0
	v_mul_f32_e32 v36, v37, v36
	v_cndmask_b32_e64 v36, v36, 0, s[4:5]
	v_bfe_u32 v37, v36, 16, 1
	v_add3_u32 v36, v36, v37, s64
	ds_write_b16_d16_hi v104, v36 offset:56240
	v_sub_f32_e32 v36, v0, v10
	v_mul_f32_e32 v36, 0x3fb8aa3b, v36
	v_exp_f32_e32 v36, v36
	v_sub_f32_e32 v0, v0, v11
	v_mul_f32_e32 v0, 0x3fb8aa3b, v0
	v_exp_f32_e32 v0, v0
	v_mul_f32_e32 v36, v38, v36
	v_cndmask_b32_e64 v36, v36, 0, s[84:85]
	v_bfe_u32 v37, v36, 16, 1
	v_mul_f32_e32 v0, v39, v0
	v_add3_u32 v36, v36, v37, s64
	v_cndmask_b32_e64 v0, v0, 0, s[36:37]
	ds_write_b16_d16_hi v104, v36 offset:56512
	v_bfe_u32 v36, v0, 16, 1
	v_add3_u32 v0, v0, v36, s64
	v_mov_b32_e32 v36, 0
	v_mov_b32_e32 v38, 0
	v_mov_b32_e32 v39, 0
	ds_write_b16_d16_hi v104, v0 offset:56784
	s_and_saveexec_b64 s[56:57], s[40:41]
	s_cbranch_execz .LBB0_1264
	v_or_b32_e32 v0, s38, v78
	v_mad_u64_u32 v[46:47], s[58:59], v0, s63, v[2:3]
	v_add_u32_e32 v47, s14, v47
	global_load_dwordx4 v[38:41], v[46:47], off
	global_load_dwordx4 v[42:45], v[46:47], off offset:64
	global_load_dwordx4 v[148:151], v[46:47], off offset:128
	global_load_dwordx4 v[152:155], v[46:47], off offset:192
	global_load_dwordx4 v[156:159], v[46:47], off offset:256
	global_load_dwordx4 v[160:163], v[46:47], off offset:320
	s_waitcnt vmcnt(0) lgkmcnt(0)
	v_mfma_f32_16x16x32_bf16 v[38:41], v[32:35], v[38:41], 0
	v_mfma_f32_16x16x32_bf16 v[38:41], v[28:31], v[42:45], v[38:41]
	v_mfma_f32_16x16x32_bf16 v[38:41], v[24:27], v[148:151], v[38:41]
	v_mfma_f32_16x16x32_bf16 v[38:41], v[20:23], v[152:155], v[38:41]
	v_mfma_f32_16x16x32_bf16 v[38:41], v[16:19], v[156:159], v[38:41]
	v_mfma_f32_16x16x32_bf16 v[38:41], v[12:15], v[160:163], v[38:41]
.LBB0_1264:
	s_or_b64 exec, exec, s[56:57]
	ds_read_b32 v0, v75 offset:51584
	v_readlane_b32 s40, v252, 28
	v_readlane_b32 s41, v252, 29
	s_waitcnt lgkmcnt(0)
	v_sub_f32_e32 v37, v0, v8
	v_mul_f32_e32 v37, 0x3fb8aa3b, v37
	v_exp_f32_e32 v37, v37
	s_nop 0
	v_mul_f32_e32 v37, v38, v37
	v_cndmask_b32_e64 v37, v37, 0, s[2:3]
	v_bfe_u32 v38, v37, 16, 1
	v_add3_u32 v37, v37, v38, s64
	ds_write_b16_d16_hi v104, v37 offset:56000
	v_sub_f32_e32 v37, v0, v9
	v_mul_f32_e32 v37, 0x3fb8aa3b, v37
	v_exp_f32_e32 v37, v37
	s_nop 0
	v_mul_f32_e32 v37, v39, v37
	v_cndmask_b32_e64 v37, v37, 0, s[0:1]
	v_bfe_u32 v38, v37, 16, 1
	v_add3_u32 v37, v37, v38, s64
	ds_write_b16_d16_hi v104, v37 offset:56272
	v_sub_f32_e32 v37, v0, v10
	v_mul_f32_e32 v37, 0x3fb8aa3b, v37
	v_exp_f32_e32 v37, v37
	v_sub_f32_e32 v0, v0, v11
	v_mul_f32_e32 v0, 0x3fb8aa3b, v0
	v_exp_f32_e32 v0, v0
	v_mul_f32_e32 v37, v40, v37
	v_cndmask_b32_e64 v37, v37, 0, s[78:79]
	v_bfe_u32 v38, v37, 16, 1
	v_mul_f32_e32 v0, v41, v0
	v_add3_u32 v37, v37, v38, s64
	v_cndmask_b32_e64 v0, v0, 0, s[66:67]
	ds_write_b16_d16_hi v104, v37 offset:56544
	v_bfe_u32 v37, v0, 16, 1
	v_add3_u32 v0, v0, v37, s64
	v_mov_b32_e32 v37, 0
	v_mov_b32_e32 v38, 0
	v_mov_b32_e32 v39, 0
	ds_write_b16_d16_hi v104, v0 offset:56816
	s_and_saveexec_b64 s[56:57], s[40:41]
	s_cbranch_execz .LBB0_1266
	v_or_b32_e32 v0, s38, v80
	v_mad_u64_u32 v[2:3], s[38:39], v0, s63, v[2:3]
	v_add_u32_e32 v3, s14, v3
	global_load_dwordx4 v[148:151], v[2:3], off
	global_load_dwordx4 v[152:155], v[2:3], off offset:64
	global_load_dwordx4 v[156:159], v[2:3], off offset:128
	global_load_dwordx4 v[160:163], v[2:3], off offset:192
	global_load_dwordx4 v[164:167], v[2:3], off offset:256
	global_load_dwordx4 v[168:171], v[2:3], off offset:320
	s_waitcnt vmcnt(0) lgkmcnt(0)
	v_mfma_f32_16x16x32_bf16 v[32:35], v[32:35], v[148:151], 0
	v_mfma_f32_16x16x32_bf16 v[28:31], v[28:31], v[152:155], v[32:35]
	v_mfma_f32_16x16x32_bf16 v[24:27], v[24:27], v[156:159], v[28:31]
	v_mfma_f32_16x16x32_bf16 v[20:23], v[20:23], v[160:163], v[24:27]
	v_mfma_f32_16x16x32_bf16 v[16:19], v[16:19], v[164:167], v[20:23]
	v_mfma_f32_16x16x32_bf16 v[36:39], v[12:15], v[168:171], v[16:19]

.LBB0_1270:
	s_mov_b64 s[68:69], 0x6000
	global_load_dwordx4 v[232:235], v[2:3], off
	v_lshl_add_u64 v[2:3], v[2:3], 0, s[68:69]
	global_load_dwordx4 v[236:239], v[2:3], off
	v_lshl_add_u64 v[2:3], v[2:3], 0, s[68:69]
	global_load_dwordx4 v[240:243], v[2:3], off
	v_lshl_add_u64 v[2:3], v[2:3], 0, s[68:69]
	v_cmp_gt_u32_e32 vcc, 0x80, v176
	s_and_saveexec_b64 s[56:57], vcc
	global_load_dwordx4 v[244:247], v[2:3], off
	s_waitcnt vmcnt(0)
	ds_write_b128 v0, v[244:247] offset:27648
	s_or_b64 exec, exec, s[56:57]
	s_waitcnt vmcnt(0)
	ds_write_b128 v0, v[232:235]
	ds_write_b128 v0, v[236:239] offset:9216
	ds_write_b128 v0, v[240:243] offset:18432
	s_movk_i32 s68, 0x47f
	s_or_b64 exec, exec, s[56:57]
	v_lshl_add_u32 v0, v92, 7, v71
	s_waitcnt lgkmcnt(0)
	s_barrier
	ds_read_b128 v[92:95], v0
	ds_read_b128 v[180:183], v105
	ds_read_b128 v[184:187], v106
	ds_read_b128 v[188:191], v106 offset:2304
	ds_read_b128 v[192:195], v106 offset:4608
	ds_read_b128 v[196:199], v106 offset:6912
	ds_read_b128 v[200:203], v106 offset:9216
	ds_read_b128 v[204:207], v106 offset:11520
	ds_read_b128 v[208:211], v106 offset:13824
	ds_read_b128 v[212:215], v105 offset:18432
	ds_read_b128 v[216:219], v105 offset:20736
	ds_read_b128 v[220:223], v105 offset:23040
	ds_read_b128 v[224:227], v105 offset:25344
	ds_read_b128 v[228:231], v105 offset:27648
	s_add_i32 s56, s61, 1
	s_cmp_gt_u32 s61, 4
	s_waitcnt lgkmcnt(12)
	v_mfma_f32_16x16x32_bf16 v[8:11], v[92:95], v[180:183], v[8:11]
	s_waitcnt lgkmcnt(11)
	v_mfma_f32_16x16x32_bf16 v[12:15], v[92:95], v[184:187], v[12:15]
	s_waitcnt lgkmcnt(10)
	v_mfma_f32_16x16x32_bf16 v[16:19], v[92:95], v[188:191], v[16:19]
	s_waitcnt lgkmcnt(9)
	v_mfma_f32_16x16x32_bf16 v[20:23], v[92:95], v[192:195], v[20:23]
	s_waitcnt lgkmcnt(8)
	v_mfma_f32_16x16x32_bf16 v[24:27], v[92:95], v[196:199], v[24:27]
	s_waitcnt lgkmcnt(7)
	v_mfma_f32_16x16x32_bf16 v[28:31], v[92:95], v[200:203], v[28:31]
	s_waitcnt lgkmcnt(6)
	v_mfma_f32_16x16x32_bf16 v[32:35], v[92:95], v[204:207], v[32:35]
	s_waitcnt lgkmcnt(5)
	v_mfma_f32_16x16x32_bf16 v[36:39], v[92:95], v[208:211], v[36:39]
	s_waitcnt lgkmcnt(4)
	v_mfma_f32_16x16x32_bf16 v[40:43], v[92:95], v[212:215], v[40:43]
	s_waitcnt lgkmcnt(3)
	v_mfma_f32_16x16x32_bf16 v[44:47], v[92:95], v[216:219], v[44:47]
	s_waitcnt lgkmcnt(2)
	v_mfma_f32_16x16x32_bf16 v[48:51], v[92:95], v[220:223], v[48:51]
	s_waitcnt lgkmcnt(1)
	v_mfma_f32_16x16x32_bf16 v[52:55], v[92:95], v[224:227], v[52:55]
	s_waitcnt lgkmcnt(0)
	v_mfma_f32_16x16x32_bf16 v[56:59], v[92:95], v[228:231], v[56:59]
	ds_read_b128 v[92:95], v0 offset:64
	ds_read_b128 v[180:183], v105 offset:64
	ds_read_b128 v[184:187], v106 offset:64
	ds_read_b128 v[188:191], v106 offset:2368
	ds_read_b128 v[192:195], v106 offset:4672
	ds_read_b128 v[196:199], v106 offset:6976
	ds_read_b128 v[200:203], v106 offset:9280
	ds_read_b128 v[204:207], v106 offset:11584
	ds_read_b128 v[208:211], v106 offset:13888
	ds_read_b128 v[212:215], v105 offset:18496
	ds_read_b128 v[216:219], v105 offset:20800
	ds_read_b128 v[220:223], v105 offset:23104
	ds_read_b128 v[224:227], v105 offset:25408
	ds_read_b128 v[228:231], v105 offset:27712
	s_waitcnt lgkmcnt(12)
	v_mfma_f32_16x16x32_bf16 v[8:11], v[92:95], v[180:183], v[8:11]
	s_waitcnt lgkmcnt(11)
	v_mfma_f32_16x16x32_bf16 v[12:15], v[92:95], v[184:187], v[12:15]
	s_waitcnt lgkmcnt(10)
	v_mfma_f32_16x16x32_bf16 v[16:19], v[92:95], v[188:191], v[16:19]
	s_waitcnt lgkmcnt(9)
	v_mfma_f32_16x16x32_bf16 v[20:23], v[92:95], v[192:195], v[20:23]
	s_waitcnt lgkmcnt(8)
	v_mfma_f32_16x16x32_bf16 v[24:27], v[92:95], v[196:199], v[24:27]
	s_waitcnt lgkmcnt(7)
	v_mfma_f32_16x16x32_bf16 v[28:31], v[92:95], v[200:203], v[28:31]
	s_waitcnt lgkmcnt(6)
	v_mfma_f32_16x16x32_bf16 v[32:35], v[92:95], v[204:207], v[32:35]
	s_waitcnt lgkmcnt(5)
	v_mfma_f32_16x16x32_bf16 v[36:39], v[92:95], v[208:211], v[36:39]
	s_waitcnt lgkmcnt(4)
	v_mfma_f32_16x16x32_bf16 v[40:43], v[92:95], v[212:215], v[40:43]
	s_waitcnt lgkmcnt(3)
	v_mfma_f32_16x16x32_bf16 v[44:47], v[92:95], v[216:219], v[44:47]
	s_waitcnt lgkmcnt(2)
	v_mfma_f32_16x16x32_bf16 v[48:51], v[92:95], v[220:223], v[48:51]
	s_waitcnt lgkmcnt(1)
	v_mfma_f32_16x16x32_bf16 v[52:55], v[92:95], v[224:227], v[52:55]
	s_waitcnt lgkmcnt(0)
	v_mfma_f32_16x16x32_bf16 v[56:59], v[92:95], v[228:231], v[56:59]
	s_cbranch_scc1 .LBB0_1273
	s_mov_b32 s61, s56
	s_branch .LBB0_1267

.LBB0_1276:
	s_mov_b64 s[56:57], 0x4000
	global_load_dwordx4 v[232:235], v[90:91], off
	v_lshl_add_u64 v[90:91], v[90:91], 0, s[56:57]
	global_load_dwordx4 v[236:239], v[90:91], off
	v_lshl_add_u64 v[90:91], v[90:91], 0, s[56:57]
	global_load_dwordx4 v[240:243], v[90:91], off
	s_waitcnt vmcnt(0)
	ds_write_b128 v0, v[232:235]
	ds_write_b128 v0, v[236:239] offset:9216
	ds_write_b128 v0, v[240:243] offset:18432
	s_movk_i32 s56, 0x3ff
	s_or_b64 exec, exec, s[38:39]
	s_lshl_b32 s38, s14, 1
	v_cmp_le_u32_e32 vcc, s38, v69
	s_waitcnt lgkmcnt(0)
	s_barrier
	s_and_saveexec_b64 s[38:39], vcc
	s_cbranch_execz .LBB0_1274
	v_lshl_add_u32 v0, s14, 7, v63
	ds_read_b128 v[90:93], v0 offset:55808
	ds_read_b128 v[94:97], v105
	s_waitcnt lgkmcnt(1)
	v_mfma_f32_16x16x32_bf16 v[56:59], v[90:93], v[4:7], v[56:59]
	s_waitcnt lgkmcnt(0)
	v_mfma_f32_16x16x32_bf16 v[8:11], v[90:93], v[94:97], v[8:11]
	ds_read_b128 v[180:183], v106
	ds_read_b128 v[184:187], v106 offset:2304
	ds_read_b128 v[188:191], v106 offset:4608
	ds_read_b128 v[192:195], v106 offset:6912
	ds_read_b128 v[196:199], v106 offset:9216
	ds_read_b128 v[200:203], v106 offset:11520
	ds_read_b128 v[204:207], v106 offset:13824
	ds_read_b128 v[208:211], v105 offset:18432
	ds_read_b128 v[212:215], v105 offset:20736
	ds_read_b128 v[216:219], v105 offset:23040
	ds_read_b128 v[220:223], v105 offset:25344
	s_waitcnt lgkmcnt(10)
	v_mfma_f32_16x16x32_bf16 v[12:15], v[90:93], v[180:183], v[12:15]
	s_waitcnt lgkmcnt(9)
	v_mfma_f32_16x16x32_bf16 v[16:19], v[90:93], v[184:187], v[16:19]
	s_waitcnt lgkmcnt(8)
	v_mfma_f32_16x16x32_bf16 v[20:23], v[90:93], v[188:191], v[20:23]
	s_waitcnt lgkmcnt(7)
	v_mfma_f32_16x16x32_bf16 v[24:27], v[90:93], v[192:195], v[24:27]
	s_waitcnt lgkmcnt(6)
	v_mfma_f32_16x16x32_bf16 v[28:31], v[90:93], v[196:199], v[28:31]
	s_waitcnt lgkmcnt(5)
	v_mfma_f32_16x16x32_bf16 v[32:35], v[90:93], v[200:203], v[32:35]
	s_waitcnt lgkmcnt(4)
	v_mfma_f32_16x16x32_bf16 v[36:39], v[90:93], v[204:207], v[36:39]
	s_waitcnt lgkmcnt(3)
	v_mfma_f32_16x16x32_bf16 v[40:43], v[90:93], v[208:211], v[40:43]
	s_waitcnt lgkmcnt(2)
	v_mfma_f32_16x16x32_bf16 v[44:47], v[90:93], v[212:215], v[44:47]
	s_waitcnt lgkmcnt(1)
	v_mfma_f32_16x16x32_bf16 v[48:51], v[90:93], v[216:219], v[48:51]
	s_waitcnt lgkmcnt(0)
	v_mfma_f32_16x16x32_bf16 v[52:55], v[90:93], v[220:223], v[52:55]
	ds_read_b128 v[90:93], v0 offset:55872
	ds_read_b128 v[180:183], v105 offset:64
	ds_read_b128 v[184:187], v106 offset:64
	ds_read_b128 v[188:191], v106 offset:2368
	ds_read_b128 v[192:195], v106 offset:4672
	ds_read_b128 v[196:199], v106 offset:6976
	ds_read_b128 v[200:203], v106 offset:9280
	ds_read_b128 v[204:207], v106 offset:11584
	ds_read_b128 v[208:211], v106 offset:13888
	ds_read_b128 v[212:215], v105 offset:18496
	ds_read_b128 v[216:219], v105 offset:20800
	ds_read_b128 v[220:223], v105 offset:23104
	ds_read_b128 v[224:227], v105 offset:25408
	s_waitcnt lgkmcnt(11)
	v_mfma_f32_16x16x32_bf16 v[8:11], v[90:93], v[180:183], v[8:11]
	s_waitcnt lgkmcnt(10)
	v_mfma_f32_16x16x32_bf16 v[12:15], v[90:93], v[184:187], v[12:15]
	s_waitcnt lgkmcnt(9)
	v_mfma_f32_16x16x32_bf16 v[16:19], v[90:93], v[188:191], v[16:19]
	s_waitcnt lgkmcnt(8)
	v_mfma_f32_16x16x32_bf16 v[20:23], v[90:93], v[192:195], v[20:23]
	s_waitcnt lgkmcnt(7)
	v_mfma_f32_16x16x32_bf16 v[24:27], v[90:93], v[196:199], v[24:27]
	s_waitcnt lgkmcnt(6)
	v_mfma_f32_16x16x32_bf16 v[28:31], v[90:93], v[200:203], v[28:31]
	s_waitcnt lgkmcnt(5)
	v_mfma_f32_16x16x32_bf16 v[32:35], v[90:93], v[204:207], v[32:35]
	s_waitcnt lgkmcnt(4)
	v_mfma_f32_16x16x32_bf16 v[36:39], v[90:93], v[208:211], v[36:39]
	s_waitcnt lgkmcnt(3)
	v_mfma_f32_16x16x32_bf16 v[40:43], v[90:93], v[212:215], v[40:43]
	s_waitcnt lgkmcnt(2)
	v_mfma_f32_16x16x32_bf16 v[44:47], v[90:93], v[216:219], v[44:47]
	s_waitcnt lgkmcnt(1)
	v_mfma_f32_16x16x32_bf16 v[48:51], v[90:93], v[220:223], v[48:51]
	s_waitcnt lgkmcnt(0)
	v_mfma_f32_16x16x32_bf16 v[52:55], v[90:93], v[224:227], v[52:55]
	v_mfma_f32_16x16x32_bf16 v[56:59], v[90:93], v[4:7], v[56:59]
	s_branch .LBB0_1274
